# up-GEMM epilogue: sigmoid denominators formed with one packed add per register pair (v_pk_add_f32) instead of two scalar adds
# speedup vs baseline: 1.0039x; 1.0039x over previous
; #define PG8_LAS __attribute__((address_space(3)))
; #define PG8_STAGE(bufoff, gbase, voff) do { _Pragma("unroll") for (int _i = 0; _i < 2; ++_i) \
;         __builtin_amdgcn_global_load_lds((const unsigned*)((const char*)(gbase) + (voff)[_i]), (PG8_LAS unsigned*)(lds + (bufoff) + ldsw + _i * 8192), 16, 0, 0); } while (0)
; #define PG8_WAIT_V(n) asm volatile("s_waitcnt vmcnt(" #n ")" ::: "memory")
; #define PG8_BAR __builtin_amdgcn_s_barrier()
; template <class Epi, class Sched, bool ALIGN_EPI = false, bool SP2 = false>
; __device__ __forceinline__ void gemm_phase(PG8_LAS unsigned char* lds, const Gemm g, const Sched& S, const Epi& E) {
;     ...
;         PG8_STAGE(PG8_SB(0, 0), cB, voffB); PG8_STAGE(PG8_SB(0, 1), cB + hstep, voffB); PG8_STAGE(PG8_SA(0, 0), cA, voffA); PG8_STAGE(PG8_SA(0, 1), cA + hstep, voffA);
;         if (wr == 1) PG8_BAR;
;         PG8_WAIT_V(2); PG8_BAR;
;         PG8_STAGE(PG8_SB(1, 0), cB + kstep, voffB); PG8_STAGE(PG8_SA(1, 0), cA + kstep, voffA); PG8_STAGE(PG8_SB(1, 1), cB + hstep + kstep, voffB);
;         PG8_WAIT_V(6); PG8_BAR;
;     } else {
;         PG8_STAGE(PG8_SB(0, 0), cB, voffB); PG8_STAGE(PG8_SA(0, 0), cA, voffA); PG8_STAGE(PG8_SB(0, 1), cB + hstep, voffB); PG8_STAGE(PG8_SA(0, 1), cA + hstep, voffA);
;         if (wr == 1) PG8_BAR;
;         PG8_WAIT_V(4); PG8_BAR;
;         PG8_STAGE(PG8_SB(1, 0), cB + kstep, voffB); PG8_STAGE(PG8_SA(1, 0), cA + kstep, voffA); PG8_STAGE(PG8_SB(1, 1), cB + hstep + kstep, voffB);
;         PG8_WAIT_V(6); PG8_BAR;
;     __device__ __forceinline__ void operator()(f32x4 (&acc)[2][2][4][2], const pg8::Unit& u, int wr, int wc, int fr, int fq) const {
;         const int colj = u.pn * 128 + wc * 32 + 8 * fq;
;         PG8_LAS unsigned char* wl = WL + (wr * 4 + wc) * 1024;
;         {
;             const int l = fq * 16 + fr, p = l >> 4, bj = (l >> 3) & 1, c4 = (l & 7) * 4;
;             const float* srcp = (p < 3 ? FW + p * NUP : FB) + bj * DFF + u.pn * 128 + wc * 32 + c4;
;             *(PG8_LAS f32x4*)(wl + l * 16) = *(const f32x4*)srcp;
.LBB0_739:
	s_add_u32 s28, s16, 0xa000000
	s_mov_b64 s[30:31], 0x80
	s_addc_u32 s29, s17, 0
	s_and_b32 s5, s5, 3
	s_add_i32 m0, s35, 0x18000
	v_lshl_add_u64 v[6:7], v[6:7], 0, s[30:31]
	s_sext_i32_i16 s66, s0
	s_lshl_b32 s0, s4, 13
	s_lshl_b32 s12, s5, 12
	s_waitcnt vmcnt(2)
	s_barrier
	global_load_lds_dwordx4 v[6:7], off
	v_lshl_add_u64 v[4:5], v[4:5], 0, s[30:31]
	s_add_i32 m0, s35, 0x1a000
	s_add_i32 s54, s35, 0x8000
	s_add_i32 s55, s35, 0xa000
	global_load_lds_dwordx4 v[4:5], off
	v_lshl_add_u64 v[0:1], v[0:1], 0, s[30:31]
	s_mov_b32 m0, s54
	s_add_u32 s6, s10, 0x40080
	global_load_lds_dwordx4 v[0:1], off
	v_lshl_add_u64 v[0:1], v[2:3], 0, s[30:31]
	s_mov_b32 m0, s55
	s_addc_u32 s7, s11, 0
	global_load_lds_dwordx4 v[0:1], off
	s_add_i32 m0, s35, 0x1c000
	v_lshl_add_u64 v[0:1], s[6:7], 0, v[132:133]
	global_load_lds_dwordx4 v[0:1], off
	v_lshl_add_u64 v[0:1], s[6:7], 0, v[128:129]
	s_add_i32 m0, s35, 0x1e000
	v_lshrrev_b32_e32 v14, 4, v152
	global_load_lds_dwordx4 v[0:1], off
	v_and_b32_e32 v169, 15, v152
	v_bfe_u32 v239, v152, 3, 1
	v_mul_u32_u24_e32 v239, 0x873823, v239
	v_sub_u32_e32 v239, 0xbfb8aa3b, v239
	v_mov_b32_e32 v250, 1.0
	v_mov_b32_e32 v251, 1.0
	s_nop 0
	s_nop 0
	s_nop 0
	s_nop 0
	s_nop 0
	s_nop 0
	s_nop 0
	s_nop 0
	v_and_b32_e32 v15, 3, v14
	v_lshlrev_b32_e32 v14, 4, v15
	s_waitcnt vmcnt(0)
	v_lshlrev_b32_e32 v18, 2, v169
	v_lshl_or_b32 v17, v169, 6, v14
	v_and_b32_e32 v19, 32, v18
	s_cmpk_lt_u32 s1, 0x100
	v_bitop3_b32 v4, v17, s0, v19 bitop3:0xde
	v_lshlrev_b32_e32 v0, 6, v152
	s_movk_i32 s0, 0x3c0
	v_lshlrev_b32_e32 v1, 2, v152
	s_cselect_b64 s[84:85], -1, 0
	s_lshl_b32 s24, s4, 12
	v_and_or_b32 v0, v0, s0, v14
	v_and_b32_e32 v1, 32, v1
	s_lshl_b32 s38, s5, 10
	v_lshl_or_b32 v187, s4, 6, v18
	s_lshl_b32 s57, s4, 2
	s_add_i32 s4, s24, 0
	v_bitop3_b32 v171, s12, v0, v1 bitop3:0xf6
	v_bfe_u32 v0, v152, 3, 1
	v_mul_u32_u24_e32 v1, 0x1600, v15
	s_add_i32 s4, s4, s38
	v_readlane_b32 s36, v253, 18
	v_mul_u32_u24_e32 v2, 0xb00, v0
	v_lshlrev_b32_e32 v0, 2, v1
	v_mov_b32_e32 v1, v133
	v_readlane_b32 s46, v253, 28
	v_readlane_b32 s47, v253, 29
	v_readlane_b32 s49, v253, 31
	v_readlane_b32 s48, v253, 30
	v_lshl_add_u64 v[0:1], s[46:47], 0, v[0:1]
	v_mov_b32_e32 v3, s49
	v_cmp_eq_u32_e32 vcc, 3, v15
	v_lshlrev_b32_e32 v2, 2, v2
	v_lshlrev_b32_e32 v5, 4, v169
	v_cndmask_b32_e32 v1, v1, v3, vcc
	v_mov_b32_e32 v3, s48
	v_cndmask_b32_e32 v0, v0, v3, vcc
	v_mov_b32_e32 v3, v133
	v_lshl_add_u64 v[0:1], v[0:1], 0, v[2:3]
	s_lshl_b32 s24, s5, 7
	v_lshl_add_u64 v[0:1], v[0:1], 0, s[24:25]
	v_and_b32_e32 v2, 0x70, v5
	v_lshl_add_u64 v[136:137], v[0:1], 0, v[2:3]
	v_add3_u32 v0, v13, v10, v12
	v_lshl_or_b32 v0, v0, 11, v8
	s_mov_b64 s[12:13], 0x40080
	v_add_u32_e32 v0, v0, v9
	v_mov_b32_e32 v1, v133
	v_lshl_add_u64 v[140:141], v[0:1], 0, s[12:13]
	v_add3_u32 v0, v11, v10, v12
	v_lshl_or_b32 v0, v0, 11, v8
	s_waitcnt vmcnt(6)
	s_add_i32 s4, s4, 0x20100
	v_add_u32_e32 v0, v0, v9
	v_lshlrev_b32_e32 v16, 3, v15
	v_lshlrev_b32_e32 v6, 5, v15
	v_cmp_eq_u32_e64 s[6:7], 0, v169
	v_readlane_b32 s38, v253, 20
	v_lshl_add_u32 v2, v15, 8, s4
	v_mov_b32_e32 v15, v133
	v_lshl_add_u64 v[142:143], v[0:1], 0, s[12:13]
	s_add_i32 s61, 0, 0x10000
	s_add_i32 s62, 0, 0x14000
	v_mbcnt_lo_u32_b32 v0, -1, 0
	v_lshl_or_b32 v186, s5, 5, v16
	s_movk_i32 s56, 0x1600
	v_cmp_ne_u32_e64 s[0:1], 0, v169
	v_cndmask_b32_e64 v188, 2, 0, s[6:7]
	v_cndmask_b32_e64 v189, 3, 1, s[6:7]
	s_add_i32 s58, s57, 8
	s_ashr_i32 s59, s80, 31
	s_mov_b32 s60, s80
	v_readlane_b32 s40, v253, 22
	v_readlane_b32 s42, v253, 24
	v_lshl_add_u64 v[138:139], s[20:21], 0, v[14:15]
	v_mov_b64_e32 v[144:145], 0xb00
	v_mov_b64_e32 v[146:147], 0xaff
	v_add_u32_e32 v190, s61, v171
	v_add_u32_e32 v191, s62, v171
	v_add_u32_e32 v192, 0, v4
	v_add_u32_e32 v193, v2, v5
	v_mbcnt_hi_u32_b32 v194, -1, v0
	s_mov_b32 s24, 0x3a800000
	s_mov_b32 s38, 0x358637bd
	s_mov_b32 s63, 0x800000
	s_movk_i32 s64, 0x2c00
	s_movk_i32 s65, 0x1000
	v_add_u32_e32 v195, s4, v6
	s_barrier
	v_readlane_b32 s37, v253, 19
	v_readlane_b32 s39, v253, 21
	v_readlane_b32 s41, v253, 23
	v_readlane_b32 s43, v253, 25
	v_readlane_b32 s44, v253, 26
	v_readlane_b32 s45, v253, 27
	v_readlane_b32 s50, v253, 32
	v_readlane_b32 s51, v253, 33
	s_branch .LBB0_742

; #define PG8_LAS __attribute__((address_space(3)))
;     __device__ __forceinline__ void operator()(f32x4 (&acc)[2][2][4][2], const pg8::Unit& u, int wr, int wc, int fr, int fq) const {
;     ...
;         PG8_LAS unsigned char* wl = WL + (wr * 4 + wc) * 1024;
;         {
;             const int l = fq * 16 + fr, p = l >> 4, bj = (l >> 3) & 1, c4 = (l & 7) * 4;
;             const float* srcp = (p < 3 ? FW + p * NUP : FB) + bj * DFF + u.pn * 128 + wc * 32 + c4;
;             *(PG8_LAS f32x4*)(wl + l * 16) = *(const f32x4*)srcp;
;         }
; #pragma unroll
;         for (int ai = 0; ai < 2; ++ai) {
;             const int tb = u.pm * 256 + ai * 128 + wr * 64 + 4 * fr;
;             float rstd[4];
; #pragma unroll
;             for (int m = 0; m < 4; ++m) { const f32x4 sv = *(const f32x4*)(SS + (size_t)(tb + m) * 16 + 4 * fq); float s = (sv[0] + sv[1]) + (sv[2] + sv[3]); s += __shfl_xor(s, 16); s += __shfl_xor(s, 32);
;                 rstd[m] = rsqrtf(s * (1.0f / 1024.0f) + EPS); }
;             u32x2 pk[2][4];
; #pragma unroll
;             for (int n = 0; n < 2; ++n) {
;                 f32x4 g[4];
;                 {   const PG8_LAS unsigned char* wq = wl + (8 * fq + 4 * n) * 4;
;                     const f32x4 w0 = *(const PG8_LAS f32x4*)(wq), w1 = *(const PG8_LAS f32x4*)(wq + 256), w2 = *(const PG8_LAS f32x4*)(wq + 512), bb = *(const PG8_LAS f32x4*)(wq + 768);
;                     const f32x4 x0 = acc[ai][0][0][n] * rstd[0], x1 = acc[ai][0][1][n] * rstd[1], x2 = acc[ai][0][2][n] * rstd[2], x3 = acc[ai][0][3][n] * rstd[3];
.LBB0_748:
	v_lshl_add_u32 v148, s34, 8, v187
	v_ashrrev_i32_e32 v149, 31, v148
	v_lshlrev_b64 v[150:151], 6, v[148:149]
	v_lshl_add_u64 v[154:155], v[138:139], 0, v[150:151]
	v_or_b32_e32 v150, 1, v148
	v_ashrrev_i32_e32 v151, 31, v150
	v_lshlrev_b64 v[156:157], 6, v[150:151]
	v_lshl_add_u64 v[156:157], v[138:139], 0, v[156:157]
	global_load_dwordx4 v[160:163], v[154:155], off
	global_load_dwordx4 v[164:167], v[156:157], off
	v_or_b32_e32 v154, 2, v148
	v_ashrrev_i32_e32 v155, 31, v154
	v_lshlrev_b64 v[156:157], 6, v[154:155]
	v_lshl_add_u64 v[156:157], v[138:139], 0, v[156:157]
	global_load_dwordx4 v[172:175], v[156:157], off
	v_or_b32_e32 v156, 3, v148
	v_ashrrev_i32_e32 v157, 31, v156
	v_lshlrev_b64 v[158:159], 6, v[156:157]
	v_lshl_add_u64 v[158:159], v[138:139], 0, v[158:159]
	global_load_dwordx4 v[176:179], v[158:159], off
	s_lshl_b32 s8, s66, 7
	s_ashr_i32 s9, s8, 31
	v_lshl_add_u64 v[158:159], s[8:9], 2, v[136:137]
	global_load_dwordx4 v[180:183], v[158:159], off
	v_and_b32_e32 v151, 64, v194
	v_xor_b32_e32 v149, 16, v194
	v_add_u32_e32 v151, 64, v151
	v_cmp_lt_i32_e32 vcc, v149, v151
	v_xor_b32_e32 v155, 32, v194
	v_mov_b64_e32 v[184:185], s[38:39]
	v_cndmask_b32_e32 v149, v194, v149, vcc
	v_lshlrev_b32_e32 v149, 2, v149
	v_cmp_lt_i32_e32 vcc, v155, v151
	v_or_b32_e32 v158, s8, v186
	v_ashrrev_i32_e32 v159, 31, v158
	v_cndmask_b32_e32 v151, v194, v155, vcc
	v_lshlrev_b32_e32 v151, 2, v151
	s_waitcnt vmcnt(0)
	v_mov_b32_e32 v196, v161
	v_mov_b32_e32 v197, v162
	v_mov_b32_e32 v161, v163
	v_mov_b32_e32 v162, v165
	v_mov_b32_e32 v163, v166
	v_mov_b32_e32 v165, v167
	v_mov_b32_e32 v166, v173
	v_mov_b32_e32 v167, v174
	v_mov_b32_e32 v173, v175
	v_pk_add_f32 v[160:161], v[196:197], v[160:161]
	v_pk_add_f32 v[162:163], v[162:163], v[164:165]
	v_mov_b32_e32 v174, v177
	v_mov_b32_e32 v175, v178
	v_mov_b32_e32 v177, v179
	v_pk_add_f32 v[166:167], v[166:167], v[172:173]
	v_pk_add_f32 v[172:173], v[174:175], v[176:177]
	v_mov_b32_e32 v165, v160
	v_mov_b32_e32 v164, v162
	v_mov_b32_e32 v160, v163
	v_mov_b32_e32 v162, v172
	v_mov_b32_e32 v163, v166
	v_mov_b32_e32 v166, v173
	v_pk_add_f32 v[160:161], v[164:165], v[160:161]
	v_pk_add_f32 v[162:163], v[162:163], v[166:167]
	ds_bpermute_b32 v165, v149, v161
	ds_bpermute_b32 v164, v149, v160
	ds_bpermute_b32 v167, v149, v163
	ds_bpermute_b32 v166, v149, v162
	v_mul_f32_e32 v180, v239, v180
	v_mul_f32_e32 v181, v239, v181
	v_mul_f32_e32 v182, v239, v182
	v_mul_f32_e32 v183, v239, v183
	ds_write_b128 v193, v[180:183]
	s_waitcnt lgkmcnt(3)
	v_pk_add_f32 v[172:173], v[160:161], v[164:165]
	ds_bpermute_b32 v197, v151, v173
	s_waitcnt lgkmcnt(2)
	v_pk_add_f32 v[174:175], v[162:163], v[166:167]
	ds_bpermute_b32 v196, v151, v172
	ds_bpermute_b32 v199, v151, v175
	ds_bpermute_b32 v198, v151, v174
	ds_read_b128 v[160:163], v195
	ds_read_b128 v[164:167], v195 offset:256
	ds_read_b128 v[176:179], v195 offset:512
	ds_read_b128 v[180:183], v195 offset:768
	s_waitcnt lgkmcnt(6)
	v_pk_add_f32 v[172:173], v[172:173], v[196:197]
	s_nop 0
	v_pk_fma_f32 v[172:173], v[172:173], s[24:25], v[184:185] op_sel_hi:[1,0,0]
	s_waitcnt lgkmcnt(4)
	v_pk_add_f32 v[174:175], v[174:175], v[198:199]
	v_mul_f32_e32 v155, 0x4b800000, v173
	v_pk_fma_f32 v[174:175], v[174:175], s[24:25], v[184:185] op_sel_hi:[1,0,0]
	v_cmp_gt_f32_e32 vcc, s63, v173
	v_mul_f32_e32 v168, 0x4b800000, v175
	v_mul_f32_e32 v170, 0x4b800000, v174
	v_cmp_gt_f32_e64 s[10:11], s63, v175
	v_cmp_gt_f32_e64 s[12:13], s63, v174
	v_cndmask_b32_e32 v155, v173, v155, vcc
	v_cndmask_b32_e64 v168, v175, v168, s[10:11]
	v_cndmask_b32_e64 v170, v174, v170, s[12:13]
	v_rsq_f32_e32 v155, v155
	v_rsq_f32_e32 v168, v168
	v_rsq_f32_e32 v173, v170
	v_mul_f32_e32 v157, 0x4b800000, v172
	v_cmp_gt_f32_e64 s[8:9], s63, v172
	v_mul_f32_e32 v170, 0x45800000, v155
	v_mul_f32_e32 v175, 0x45800000, v168
	v_cndmask_b32_e64 v157, v172, v157, s[8:9]
	v_mul_f32_e32 v184, 0x45800000, v173
	v_rsq_f32_e32 v157, v157
	v_cndmask_b32_e32 v174, v155, v170, vcc
	v_cndmask_b32_e64 v170, v168, v175, s[10:11]
	v_cndmask_b32_e64 v168, v173, v184, s[12:13]
	v_pk_mul_f32 v[124:125], v[124:125], v[174:175] op_sel_hi:[1,0]
	v_pk_mul_f32 v[112:113], v[112:113], v[168:169] op_sel_hi:[1,0]
	v_pk_mul_f32 v[116:117], v[116:117], v[170:171] op_sel_hi:[1,0]
	s_waitcnt lgkmcnt(0)
; #define PG8_LAS __attribute__((address_space(3)))
; __device__ __forceinline__ float row_up1(float v) { return dpp_mov<0x111>(v); }
; __device__ __forceinline__ float siluf_(float x) { return x * __builtin_amdgcn_rcpf(1.0f + __builtin_amdgcn_exp2f(x * -1.4426950408889634f)); }
;     __device__ __forceinline__ void operator()(f32x4 (&acc)[2][2][4][2], const pg8::Unit& u, int wr, int wc, int fr, int fq) const {
;     ...
;                     const f32x4 x0 = acc[ai][0][0][n] * rstd[0], x1 = acc[ai][0][1][n] * rstd[1], x2 = acc[ai][0][2][n] * rstd[2], x3 = acc[ai][0][3][n] * rstd[3];
;                     acc[ai][0][0][n] = x0; acc[ai][0][1][n] = x1; acc[ai][0][2][n] = x2; acc[ai][0][3][n] = x3;
;                     f32x4 p1, p2;
; #pragma unroll
;                     for (int c = 0; c < 4; ++c) { p1[c] = row_up1(x3[c]); p2[c] = row_up1(x2[c]); }
;                     g[0] = bb + w2 * x0 + w1 * p1 + w0 * p2; g[1] = bb + w2 * x1 + w1 * x0 + w0 * p1;
;                     g[2] = bb + w2 * x2 + w1 * x1 + w0 * x0; g[3] = bb + w2 * x3 + w1 * x2 + w0 * x1;
; #pragma unroll
;                     for (int m = 0; m < 4; ++m)
; #pragma unroll
;                         for (int c = 0; c < 4; ++c) g[m][c] = siluf_(g[m][c]);
;                 }
;                 __builtin_amdgcn_sched_barrier(0);
;                 {   const PG8_LAS unsigned char* wq = wl + 128 + (8 * fq + 4 * n) * 4;
;                     const f32x4 w0 = *(const PG8_LAS f32x4*)(wq), w1 = *(const PG8_LAS f32x4*)(wq + 256), w2 = *(const PG8_LAS f32x4*)(wq + 512), bb = *(const PG8_LAS f32x4*)(wq + 768);
;                     const f32x4 x0 = acc[ai][1][0][n] * rstd[0], x1 = acc[ai][1][1][n] * rstd[1], x2 = acc[ai][1][2][n] * rstd[2], x3 = acc[ai][1][3][n] * rstd[3];
	v_pk_fma_f32 v[204:205], v[176:177], v[124:125], v[180:181]
	v_mov_b32_dpp v184, v112 row_shr:1 row_mask:0xf bank_mask:0xf bound_ctrl:1
	v_mov_b32_dpp v185, v113 row_shr:1 row_mask:0xf bank_mask:0xf bound_ctrl:1
	v_mov_b32_dpp v196, v116 row_shr:1 row_mask:0xf bank_mask:0xf bound_ctrl:1
	v_mov_b32_dpp v197, v117 row_shr:1 row_mask:0xf bank_mask:0xf bound_ctrl:1
	v_pk_fma_f32 v[204:205], v[164:165], v[184:185], v[204:205]
	v_mul_f32_e32 v172, 0x45800000, v157
	v_pk_fma_f32 v[196:197], v[160:161], v[196:197], v[204:205]
	v_cndmask_b32_e64 v172, v157, v172, s[8:9]
	v_pk_mul_f32 v[126:127], v[126:127], v[174:175] op_sel_hi:[1,0]
	v_pk_mul_f32 v[120:121], v[120:121], v[172:173] op_sel_hi:[1,0]
	v_pk_mul_f32 v[114:115], v[114:115], v[168:169] op_sel_hi:[1,0]
	v_exp_f32_e32 v240, v196
	v_pk_mul_f32 v[118:119], v[118:119], v[170:171] op_sel_hi:[1,0]
	v_mov_b32_dpp v198, v114 row_shr:1 row_mask:0xf bank_mask:0xf bound_ctrl:1
	v_mov_b32_dpp v199, v115 row_shr:1 row_mask:0xf bank_mask:0xf bound_ctrl:1
	v_pk_fma_f32 v[202:203], v[178:179], v[126:127], v[182:183]
	v_pk_fma_f32 v[204:205], v[176:177], v[120:121], v[180:181]
	v_exp_f32_e32 v241, v197
	v_pk_mul_f32 v[122:123], v[122:123], v[172:173] op_sel_hi:[1,0]
	v_mov_b32_dpp v200, v118 row_shr:1 row_mask:0xf bank_mask:0xf bound_ctrl:1
	v_mov_b32_dpp v201, v119 row_shr:1 row_mask:0xf bank_mask:0xf bound_ctrl:1
	v_pk_fma_f32 v[202:203], v[166:167], v[198:199], v[202:203]
	v_pk_fma_f32 v[204:205], v[164:165], v[124:125], v[204:205]
	v_pk_fma_f32 v[200:201], v[162:163], v[200:201], v[202:203]
	v_pk_fma_f32 v[202:203], v[178:179], v[122:123], v[182:183]
	v_pk_fma_f32 v[184:185], v[160:161], v[184:185], v[204:205]
	v_pk_fma_f32 v[204:205], v[176:177], v[116:117], v[180:181]
	v_pk_fma_f32 v[176:177], v[176:177], v[112:113], v[180:181]
	v_pk_fma_f32 v[202:203], v[166:167], v[126:127], v[202:203]
	v_pk_fma_f32 v[204:205], v[164:165], v[120:121], v[204:205]
	v_pk_fma_f32 v[164:165], v[164:165], v[116:117], v[176:177]
	v_pk_fma_f32 v[198:199], v[162:163], v[198:199], v[202:203]
	v_pk_fma_f32 v[202:203], v[178:179], v[118:119], v[182:183]
	v_pk_fma_f32 v[204:205], v[160:161], v[124:125], v[204:205]
	v_pk_fma_f32 v[178:179], v[178:179], v[114:115], v[182:183]
	v_pk_fma_f32 v[214:215], v[160:161], v[120:121], v[164:165]
	v_pk_add_f32 v[240:241], v[240:241], v[250:251]
	v_rcp_f32_e32 v160, v240
	v_pk_fma_f32 v[202:203], v[166:167], v[122:123], v[202:203]
	v_pk_fma_f32 v[166:167], v[166:167], v[118:119], v[178:179]
	v_exp_f32_e32 v242, v200
	v_pk_fma_f32 v[202:203], v[162:163], v[126:127], v[202:203]
	v_pk_fma_f32 v[212:213], v[162:163], v[122:123], v[166:167]
	v_exp_f32_e32 v243, v201
	v_rcp_f32_e32 v161, v241
	v_pk_add_f32 v[242:243], v[242:243], v[250:251]
	v_rcp_f32_e32 v162, v242
	v_rcp_f32_e32 v163, v243
	v_exp_f32_e32 v244, v184
	v_exp_f32_e32 v245, v185
	v_pk_mul_f32 v[216:217], v[196:197], v[160:161]
	v_pk_add_f32 v[244:245], v[244:245], v[250:251]
	v_rcp_f32_e32 v160, v244
	v_exp_f32_e32 v246, v198
	v_pk_mul_f32 v[218:219], v[200:201], v[162:163]
	v_exp_f32_e32 v247, v199
	v_rcp_f32_e32 v161, v245
	v_pk_add_f32 v[246:247], v[246:247], v[250:251]
	v_rcp_f32_e32 v162, v246
	v_rcp_f32_e32 v163, v247
	v_exp_f32_e32 v248, v204
	v_exp_f32_e32 v249, v205
	v_pk_mul_f32 v[184:185], v[184:185], v[160:161]
	v_pk_add_f32 v[248:249], v[248:249], v[250:251]
	v_rcp_f32_e32 v160, v248
	v_exp_f32_e32 v240, v202
	v_exp_f32_e32 v241, v203
	v_rcp_f32_e32 v161, v249
	v_pk_add_f32 v[240:241], v[240:241], v[250:251]
	v_rcp_f32_e32 v164, v240
	v_exp_f32_e32 v242, v214
	v_exp_f32_e32 v243, v215
	v_rcp_f32_e32 v165, v241
	v_pk_add_f32 v[242:243], v[242:243], v[250:251]
	v_rcp_f32_e32 v220, v242
	v_exp_f32_e32 v244, v212
	v_exp_f32_e32 v245, v213
	v_rcp_f32_e32 v221, v243
	v_pk_add_f32 v[244:245], v[244:245], v[250:251]
	v_rcp_f32_e32 v222, v244
	v_rcp_f32_e32 v223, v245
	v_pk_mul_f32 v[224:225], v[198:199], v[162:163]
	v_pk_mul_f32 v[226:227], v[204:205], v[160:161]
	v_pk_mul_f32 v[228:229], v[202:203], v[164:165]
	ds_read_b128 v[196:199], v195 offset:128
	ds_read_b128 v[200:203], v195 offset:384
	ds_read_b128 v[204:207], v195 offset:640
	ds_read_b128 v[208:211], v195 offset:896
	v_pk_mul_f32 v[176:177], v[108:109], v[174:175] op_sel_hi:[1,0]
	v_pk_mul_f32 v[164:165], v[96:97], v[168:169] op_sel_hi:[1,0]
	v_pk_mul_f32 v[180:181], v[100:101], v[170:171] op_sel_hi:[1,0]
	v_pk_mul_f32 v[160:161], v[104:105], v[172:173] op_sel_hi:[1,0]
	v_mov_b32_dpp v96, v164 row_shr:1 row_mask:0xf bank_mask:0xf bound_ctrl:1
	v_mov_b32_dpp v97, v165 row_shr:1 row_mask:0xf bank_mask:0xf bound_ctrl:1
	s_waitcnt lgkmcnt(0)
; #define PG8_LAS __attribute__((address_space(3)))
; __device__ __forceinline__ unsigned pk2(float a, float b) { return pg8::cvt_pk_bf16(a, b); }
; __device__ __forceinline__ float row_up1(float v) { return dpp_mov<0x111>(v); }
; __device__ __forceinline__ float siluf_(float x) { return x * __builtin_amdgcn_rcpf(1.0f + __builtin_amdgcn_exp2f(x * -1.4426950408889634f)); }
;     __device__ __forceinline__ void operator()(f32x4 (&acc)[2][2][4][2], const pg8::Unit& u, int wr, int wc, int fr, int fq) const {
;     ...
;                     g[0] = bb + w2 * x0 + w1 * p1 + w0 * p2; g[1] = bb + w2 * x1 + w1 * x0 + w0 * p1;
;                     g[2] = bb + w2 * x2 + w1 * x1 + w0 * x0; g[3] = bb + w2 * x3 + w1 * x2 + w0 * x1;
; #pragma unroll
;                     for (int m = 0; m < 4; ++m)
; #pragma unroll
;                         for (int c = 0; c < 4; ++c) g[m][c] = siluf_(g[m][c]);
;                 }
;                 __builtin_amdgcn_sched_barrier(0);
;                 {   const PG8_LAS unsigned char* wq = wl + 128 + (8 * fq + 4 * n) * 4;
;                     const f32x4 w0 = *(const PG8_LAS f32x4*)(wq), w1 = *(const PG8_LAS f32x4*)(wq + 256), w2 = *(const PG8_LAS f32x4*)(wq + 512), bb = *(const PG8_LAS f32x4*)(wq + 768);
;                     const f32x4 x0 = acc[ai][1][0][n] * rstd[0], x1 = acc[ai][1][1][n] * rstd[1], x2 = acc[ai][1][2][n] * rstd[2], x3 = acc[ai][1][3][n] * rstd[3];
;                     acc[ai][1][0][n] = x0; acc[ai][1][1][n] = x1; acc[ai][1][2][n] = x2; acc[ai][1][3][n] = x3;
;                     f32x4 p1, p2;
; #pragma unroll
;                     for (int c = 0; c < 4; ++c) { p1[c] = row_up1(x3[c]); p2[c] = row_up1(x2[c]); }
;                     g[0] *= bb + w2 * x0 + w1 * p1 + w0 * p2; g[1] *= bb + w2 * x1 + w1 * x0 + w0 * p1;
;                     g[2] *= bb + w2 * x2 + w1 * x1 + w0 * x0; g[3] *= bb + w2 * x3 + w1 * x2 + w0 * x1;
;                 }
; #pragma unroll
;                 for (int m = 0; m < 4; ++m) { pk[n][m].x = pk2(g[m][0], g[m][1]); pk[n][m].y = pk2(g[m][2], g[m][3]); }
	v_pk_fma_f32 v[108:109], v[176:177], v[204:205], v[208:209]
	v_pk_mul_f32 v[166:167], v[98:99], v[168:169] op_sel_hi:[1,0]
	v_mov_b32_dpp v98, v180 row_shr:1 row_mask:0xf bank_mask:0xf bound_ctrl:1
	v_mov_b32_dpp v99, v181 row_shr:1 row_mask:0xf bank_mask:0xf bound_ctrl:1
	v_pk_fma_f32 v[108:109], v[200:201], v[96:97], v[108:109]
	v_pk_mul_f32 v[178:179], v[110:111], v[174:175] op_sel_hi:[1,0]
	v_pk_fma_f32 v[98:99], v[196:197], v[98:99], v[108:109]
	v_pk_fma_f32 v[108:109], v[160:161], v[204:205], v[208:209]
	v_pk_mul_f32 v[182:183], v[102:103], v[170:171] op_sel_hi:[1,0]
	v_mov_b32_dpp v100, v166 row_shr:1 row_mask:0xf bank_mask:0xf bound_ctrl:1
	v_mov_b32_dpp v101, v167 row_shr:1 row_mask:0xf bank_mask:0xf bound_ctrl:1
	v_pk_fma_f32 v[110:111], v[178:179], v[206:207], v[210:211]
	v_pk_fma_f32 v[108:109], v[176:177], v[200:201], v[108:109]
	v_pk_mul_f32 v[162:163], v[106:107], v[172:173] op_sel_hi:[1,0]
	v_mov_b32_dpp v102, v182 row_shr:1 row_mask:0xf bank_mask:0xf bound_ctrl:1
	v_mov_b32_dpp v103, v183 row_shr:1 row_mask:0xf bank_mask:0xf bound_ctrl:1
	v_pk_fma_f32 v[110:111], v[202:203], v[100:101], v[110:111]
	v_pk_fma_f32 v[96:97], v[196:197], v[96:97], v[108:109]
	v_pk_fma_f32 v[108:109], v[180:181], v[204:205], v[208:209]
	v_pk_fma_f32 v[102:103], v[198:199], v[102:103], v[110:111]
	v_pk_fma_f32 v[110:111], v[162:163], v[206:207], v[210:211]
	v_pk_fma_f32 v[108:109], v[160:161], v[200:201], v[108:109]
	v_pk_fma_f32 v[110:111], v[178:179], v[202:203], v[110:111]
	v_pk_fma_f32 v[108:109], v[176:177], v[196:197], v[108:109]
	v_pk_fma_f32 v[100:101], v[198:199], v[100:101], v[110:111]
	v_pk_mul_f32 v[96:97], v[184:185], v[96:97]
	v_pk_fma_f32 v[110:111], v[182:183], v[206:207], v[210:211]
	v_pk_mul_f32 v[184:185], v[108:109], v[226:227]
	v_pk_fma_f32 v[108:109], v[164:165], v[204:205], v[208:209]
	v_pk_fma_f32 v[204:205], v[166:167], v[206:207], v[210:211]
	v_pk_fma_f32 v[110:111], v[162:163], v[202:203], v[110:111]
	v_pk_fma_f32 v[202:203], v[182:183], v[202:203], v[204:205]
	v_pk_fma_f32 v[108:109], v[180:181], v[200:201], v[108:109]
	v_pk_mul_f32 v[106:107], v[212:213], v[222:223]
	v_pk_fma_f32 v[110:111], v[178:179], v[198:199], v[110:111]
	v_pk_fma_f32 v[108:109], v[160:161], v[196:197], v[108:109]
	v_pk_fma_f32 v[196:197], v[162:163], v[198:199], v[202:203]
	v_pk_mul_f32 v[104:105], v[214:215], v[220:221]
	v_pk_mul_f32 v[102:103], v[218:219], v[102:103]
	v_pk_mul_f32 v[98:99], v[216:217], v[98:99]
	v_pk_mul_f32 v[100:101], v[224:225], v[100:101]
	v_pk_mul_f32 v[110:111], v[110:111], v[228:229]
	v_pk_mul_f32 v[106:107], v[196:197], v[106:107]
	v_pk_mul_f32 v[196:197], v[108:109], v[104:105]
	v_cvt_pk_bf16_f32 v108, v98, v99
	v_cvt_pk_bf16_f32 v109, v102, v103
	v_cvt_pk_bf16_f32 v104, v96, v97
	v_cvt_pk_bf16_f32 v105, v100, v101
	v_cvt_pk_bf16_f32 v100, v184, v185
	v_cvt_pk_bf16_f32 v101, v110, v111
	s_nop 0
	v_cvt_pk_bf16_f32 v96, v196, v197
	v_cvt_pk_bf16_f32 v97, v106, v107
	ds_read_b128 v[196:199], v195 offset:16
	ds_read_b128 v[200:203], v195 offset:272
	ds_read_b128 v[204:207], v195 offset:528
	ds_read_b128 v[208:211], v195 offset:784
	v_pk_mul_f32 v[92:93], v[92:93], v[174:175] op_sel_hi:[1,0]
	v_pk_mul_f32 v[84:85], v[84:85], v[168:169] op_sel_hi:[1,0]
	v_pk_mul_f32 v[88:89], v[88:89], v[170:171] op_sel_hi:[1,0]
	v_pk_mul_f32 v[80:81], v[80:81], v[172:173] op_sel_hi:[1,0]
	v_mov_b32_dpp v98, v84 row_shr:1 row_mask:0xf bank_mask:0xf bound_ctrl:1
	v_mov_b32_dpp v99, v85 row_shr:1 row_mask:0xf bank_mask:0xf bound_ctrl:1
	s_waitcnt lgkmcnt(0)
	v_pk_fma_f32 v[212:213], v[92:93], v[204:205], v[208:209]
	v_mov_b32_dpp v102, v88 row_shr:1 row_mask:0xf bank_mask:0xf bound_ctrl:1
	v_mov_b32_dpp v103, v89 row_shr:1 row_mask:0xf bank_mask:0xf bound_ctrl:1
	v_pk_fma_f32 v[212:213], v[200:201], v[98:99], v[212:213]
	v_pk_mul_f32 v[94:95], v[94:95], v[174:175] op_sel_hi:[1,0]
	v_pk_fma_f32 v[102:103], v[196:197], v[102:103], v[212:213]
	v_pk_mul_f32 v[86:87], v[86:87], v[168:169] op_sel_hi:[1,0]
	v_exp_f32_e32 v246, v102
	v_pk_fma_f32 v[212:213], v[80:81], v[204:205], v[208:209]
	v_exp_f32_e32 v247, v103
	v_pk_mul_f32 v[90:91], v[90:91], v[170:171] op_sel_hi:[1,0]
	v_mov_b32_dpp v106, v86 row_shr:1 row_mask:0xf bank_mask:0xf bound_ctrl:1
	v_mov_b32_dpp v107, v87 row_shr:1 row_mask:0xf bank_mask:0xf bound_ctrl:1
	v_pk_fma_f32 v[184:185], v[94:95], v[206:207], v[210:211]
	v_pk_fma_f32 v[212:213], v[92:93], v[200:201], v[212:213]
	v_mov_b32_dpp v110, v90 row_shr:1 row_mask:0xf bank_mask:0xf bound_ctrl:1
	v_mov_b32_dpp v111, v91 row_shr:1 row_mask:0xf bank_mask:0xf bound_ctrl:1
	v_pk_fma_f32 v[184:185], v[202:203], v[106:107], v[184:185]
	v_pk_fma_f32 v[98:99], v[196:197], v[98:99], v[212:213]
	v_pk_fma_f32 v[212:213], v[88:89], v[204:205], v[208:209]
	v_pk_fma_f32 v[204:205], v[84:85], v[204:205], v[208:209]
	v_pk_fma_f32 v[110:111], v[198:199], v[110:111], v[184:185]
	v_pk_fma_f32 v[212:213], v[80:81], v[200:201], v[212:213]
	v_pk_fma_f32 v[200:201], v[88:89], v[200:201], v[204:205]
	v_pk_fma_f32 v[212:213], v[92:93], v[196:197], v[212:213]
	v_pk_fma_f32 v[216:217], v[80:81], v[196:197], v[200:201]
	v_pk_add_f32 v[246:247], v[246:247], v[250:251]
	v_rcp_f32_e32 v196, v246
	v_pk_mul_f32 v[82:83], v[82:83], v[172:173] op_sel_hi:[1,0]
	v_exp_f32_e32 v248, v110
	v_pk_fma_f32 v[184:185], v[82:83], v[206:207], v[210:211]
	v_exp_f32_e32 v249, v111
	v_pk_fma_f32 v[184:185], v[94:95], v[202:203], v[184:185]
	v_rcp_f32_e32 v197, v247
	v_pk_fma_f32 v[106:107], v[198:199], v[106:107], v[184:185]
	v_pk_fma_f32 v[184:185], v[90:91], v[206:207], v[210:211]
; #define PG8_LAS __attribute__((address_space(3)))
; __device__ __forceinline__ unsigned pk2(float a, float b) { return pg8::cvt_pk_bf16(a, b); }
; __device__ __forceinline__ float row_up1(float v) { return dpp_mov<0x111>(v); }
; __device__ __forceinline__ float siluf_(float x) { return x * __builtin_amdgcn_rcpf(1.0f + __builtin_amdgcn_exp2f(x * -1.4426950408889634f)); }
;     __device__ __forceinline__ void operator()(f32x4 (&acc)[2][2][4][2], const pg8::Unit& u, int wr, int wc, int fr, int fq) const {
;     ...
;                     g[0] = bb + w2 * x0 + w1 * p1 + w0 * p2; g[1] = bb + w2 * x1 + w1 * x0 + w0 * p1;
;                     g[2] = bb + w2 * x2 + w1 * x1 + w0 * x0; g[3] = bb + w2 * x3 + w1 * x2 + w0 * x1;
; #pragma unroll
;                     for (int m = 0; m < 4; ++m)
; #pragma unroll
;                         for (int c = 0; c < 4; ++c) g[m][c] = siluf_(g[m][c]);
;                 }
;                 __builtin_amdgcn_sched_barrier(0);
;                 {   const PG8_LAS unsigned char* wq = wl + 128 + (8 * fq + 4 * n) * 4;
;                     const f32x4 w0 = *(const PG8_LAS f32x4*)(wq), w1 = *(const PG8_LAS f32x4*)(wq + 256), w2 = *(const PG8_LAS f32x4*)(wq + 512), bb = *(const PG8_LAS f32x4*)(wq + 768);
;                     const f32x4 x0 = acc[ai][1][0][n] * rstd[0], x1 = acc[ai][1][1][n] * rstd[1], x2 = acc[ai][1][2][n] * rstd[2], x3 = acc[ai][1][3][n] * rstd[3];
;                     acc[ai][1][0][n] = x0; acc[ai][1][1][n] = x1; acc[ai][1][2][n] = x2; acc[ai][1][3][n] = x3;
;                     f32x4 p1, p2;
; #pragma unroll
;                     for (int c = 0; c < 4; ++c) { p1[c] = row_up1(x3[c]); p2[c] = row_up1(x2[c]); }
;                     g[0] *= bb + w2 * x0 + w1 * p1 + w0 * p2; g[1] *= bb + w2 * x1 + w1 * x0 + w0 * p1;
;                     g[2] *= bb + w2 * x2 + w1 * x1 + w0 * x0; g[3] *= bb + w2 * x3 + w1 * x2 + w0 * x1;
;                 }
; #pragma unroll
;                 for (int m = 0; m < 4; ++m) { pk[n][m].x = pk2(g[m][0], g[m][1]); pk[n][m].y = pk2(g[m][2], g[m][3]); }
;                 __builtin_amdgcn_sched_barrier(0);
;             }
; #pragma unroll
;             for (int m = 0; m < 4; ++m) if (fr != 0 || m >= 2) {
;                 u32x4 w; w.x = pk[0][m].x; w.y = pk[0][m].y; w.z = pk[1][m].x; w.w = pk[1][m].y;
;                 *(u32x4*)(ACT + (size_t)(tb + m) * DFF + colj) = w; }
	v_pk_fma_f32 v[206:207], v[86:87], v[206:207], v[210:211]
	v_pk_fma_f32 v[184:185], v[82:83], v[202:203], v[184:185]
	v_pk_fma_f32 v[202:203], v[90:91], v[202:203], v[206:207]
	v_pk_fma_f32 v[184:185], v[94:95], v[198:199], v[184:185]
	v_pk_fma_f32 v[214:215], v[82:83], v[198:199], v[202:203]
	v_pk_add_f32 v[248:249], v[248:249], v[250:251]
	v_rcp_f32_e32 v198, v248
	v_rcp_f32_e32 v199, v249
	v_exp_f32_e32 v240, v98
	v_exp_f32_e32 v241, v99
	v_pk_mul_f32 v[102:103], v[102:103], v[196:197]
	v_pk_add_f32 v[240:241], v[240:241], v[250:251]
	v_rcp_f32_e32 v196, v240
	v_exp_f32_e32 v242, v106
	v_exp_f32_e32 v243, v107
	v_rcp_f32_e32 v197, v241
	v_pk_mul_f32 v[110:111], v[110:111], v[198:199]
	v_pk_add_f32 v[242:243], v[242:243], v[250:251]
	v_rcp_f32_e32 v198, v242
	v_rcp_f32_e32 v199, v243
	v_exp_f32_e32 v244, v212
	v_exp_f32_e32 v245, v213
	v_pk_mul_f32 v[98:99], v[98:99], v[196:197]
	v_pk_add_f32 v[244:245], v[244:245], v[250:251]
	v_rcp_f32_e32 v196, v244
	v_exp_f32_e32 v246, v184
	v_exp_f32_e32 v247, v185
	v_rcp_f32_e32 v197, v245
	v_pk_add_f32 v[246:247], v[246:247], v[250:251]
	v_rcp_f32_e32 v200, v246
	v_exp_f32_e32 v248, v216
	v_exp_f32_e32 v249, v217
	v_rcp_f32_e32 v201, v247
	v_pk_add_f32 v[248:249], v[248:249], v[250:251]
	v_rcp_f32_e32 v218, v248
	v_exp_f32_e32 v240, v214
	v_exp_f32_e32 v241, v215
	v_rcp_f32_e32 v219, v249
	v_pk_add_f32 v[240:241], v[240:241], v[250:251]
	v_rcp_f32_e32 v220, v240
	v_pk_mul_f32 v[106:107], v[106:107], v[198:199]
	v_rcp_f32_e32 v221, v241
	v_pk_mul_f32 v[212:213], v[212:213], v[196:197]
	v_pk_mul_f32 v[222:223], v[184:185], v[200:201]
	ds_read_b128 v[196:199], v195 offset:144
	ds_read_b128 v[200:203], v195 offset:400
	ds_read_b128 v[204:207], v195 offset:656
	ds_read_b128 v[208:211], v195 offset:912
	v_pk_mul_f32 v[184:185], v[66:67], v[174:175] op_sel_hi:[1,0]
	v_pk_mul_f32 v[174:175], v[64:65], v[174:175] op_sel_hi:[1,0]
	v_pk_mul_f32 v[66:67], v[68:69], v[172:173] op_sel_hi:[1,0]
	v_pk_mul_f32 v[68:69], v[76:77], v[168:169] op_sel_hi:[1,0]
	v_pk_mul_f32 v[70:71], v[70:71], v[172:173] op_sel_hi:[1,0]
	v_pk_mul_f32 v[172:173], v[74:75], v[170:171] op_sel_hi:[1,0]
	v_pk_mul_f32 v[74:75], v[72:73], v[170:171] op_sel_hi:[1,0]
	v_mov_b32_dpp v64, v68 row_shr:1 row_mask:0xf bank_mask:0xf bound_ctrl:1
	v_mov_b32_dpp v65, v69 row_shr:1 row_mask:0xf bank_mask:0xf bound_ctrl:1
	v_pk_mul_f32 v[216:217], v[216:217], v[218:219]
	s_waitcnt lgkmcnt(0)
	v_pk_fma_f32 v[218:219], v[174:175], v[204:205], v[208:209]
	v_pk_mul_f32 v[72:73], v[78:79], v[168:169] op_sel_hi:[1,0]
	v_mov_b32_dpp v76, v74 row_shr:1 row_mask:0xf bank_mask:0xf bound_ctrl:1
	v_mov_b32_dpp v77, v75 row_shr:1 row_mask:0xf bank_mask:0xf bound_ctrl:1
	v_pk_fma_f32 v[218:219], v[200:201], v[64:65], v[218:219]
	v_mov_b32_dpp v78, v72 row_shr:1 row_mask:0xf bank_mask:0xf bound_ctrl:1
	v_mov_b32_dpp v79, v73 row_shr:1 row_mask:0xf bank_mask:0xf bound_ctrl:1
	v_pk_mul_f32 v[214:215], v[214:215], v[220:221]
	v_pk_fma_f32 v[220:221], v[184:185], v[206:207], v[210:211]
	v_pk_fma_f32 v[76:77], v[196:197], v[76:77], v[218:219]
	v_mov_b32_dpp v224, v172 row_shr:1 row_mask:0xf bank_mask:0xf bound_ctrl:1
	v_mov_b32_dpp v225, v173 row_shr:1 row_mask:0xf bank_mask:0xf bound_ctrl:1
	v_pk_fma_f32 v[220:221], v[202:203], v[78:79], v[220:221]
	v_pk_mul_f32 v[76:77], v[102:103], v[76:77]
	v_pk_fma_f32 v[102:103], v[66:67], v[204:205], v[208:209]
	v_pk_fma_f32 v[218:219], v[198:199], v[224:225], v[220:221]
	v_pk_fma_f32 v[102:103], v[174:175], v[200:201], v[102:103]
	v_pk_mul_f32 v[218:219], v[110:111], v[218:219]
	v_pk_fma_f32 v[110:111], v[70:71], v[206:207], v[210:211]
	v_pk_fma_f32 v[64:65], v[196:197], v[64:65], v[102:103]
	v_pk_fma_f32 v[102:103], v[172:173], v[206:207], v[210:211]
	v_pk_fma_f32 v[110:111], v[184:185], v[202:203], v[110:111]
	v_pk_fma_f32 v[102:103], v[70:71], v[202:203], v[102:103]
	v_pk_fma_f32 v[78:79], v[198:199], v[78:79], v[110:111]
	v_pk_mul_f32 v[64:65], v[98:99], v[64:65]
	v_pk_fma_f32 v[98:99], v[74:75], v[204:205], v[208:209]
	v_pk_fma_f32 v[102:103], v[184:185], v[198:199], v[102:103]
	v_pk_mul_f32 v[78:79], v[106:107], v[78:79]
	v_pk_fma_f32 v[98:99], v[66:67], v[200:201], v[98:99]
	v_pk_mul_f32 v[220:221], v[222:223], v[102:103]
	v_pk_fma_f32 v[102:103], v[68:69], v[204:205], v[208:209]
	v_pk_fma_f32 v[106:107], v[72:73], v[206:207], v[210:211]
	v_pk_fma_f32 v[98:99], v[174:175], v[196:197], v[98:99]
	v_pk_fma_f32 v[106:107], v[172:173], v[202:203], v[106:107]
	v_pk_fma_f32 v[102:103], v[74:75], v[200:201], v[102:103]
	v_pk_mul_f32 v[98:99], v[212:213], v[98:99]
	v_pk_fma_f32 v[102:103], v[66:67], v[196:197], v[102:103]
	v_pk_fma_f32 v[106:107], v[70:71], v[198:199], v[106:107]
	v_pk_mul_f32 v[198:199], v[216:217], v[102:103]
	v_pk_mul_f32 v[196:197], v[214:215], v[106:107]
	v_cvt_pk_bf16_f32 v110, v76, v77
	v_cvt_pk_bf16_f32 v111, v218, v219
	v_cvt_pk_bf16_f32 v106, v64, v65
	v_cvt_pk_bf16_f32 v107, v78, v79
	v_cvt_pk_bf16_f32 v102, v98, v99
	v_cvt_pk_bf16_f32 v103, v220, v221
	v_cvt_pk_bf16_f32 v98, v198, v199
	s_nop 0
	v_cvt_pk_bf16_f32 v99, v196, v197
	v_lshlrev_b64 v[64:65], 1, v[158:159]
	s_and_saveexec_b64 s[8:9], s[0:1]
	s_cbranch_execz .LBB0_750
	v_mov_b64_e32 v[76:77], s[22:23]
	v_mad_i64_i32 v[78:79], s[10:11], v148, s56, v[76:77]
	v_mad_i64_i32 v[76:77], s[10:11], v150, s56, v[76:77]
	v_lshl_add_u64 v[78:79], v[78:79], 0, v[64:65]
	v_lshl_add_u64 v[76:77], v[76:77], 0, v[64:65]
	global_store_dwordx4 v[78:79], v[108:111], off
	global_store_dwordx4 v[76:77], v[104:107], off

; #define PG8_LAS __attribute__((address_space(3)))
; __device__ __forceinline__ float row_up1(float v) { return dpp_mov<0x111>(v); }
;     __device__ __forceinline__ void operator()(f32x4 (&acc)[2][2][4][2], const pg8::Unit& u, int wr, int wc, int fr, int fq) const {
;     ...
;         for (int ai = 0; ai < 2; ++ai) {
;             const int tb = u.pm * 256 + ai * 128 + wr * 64 + 4 * fr;
;             float rstd[4];
; #pragma unroll
;             for (int m = 0; m < 4; ++m) { const f32x4 sv = *(const f32x4*)(SS + (size_t)(tb + m) * 16 + 4 * fq); float s = (sv[0] + sv[1]) + (sv[2] + sv[3]); s += __shfl_xor(s, 16); s += __shfl_xor(s, 32);
;                 rstd[m] = rsqrtf(s * (1.0f / 1024.0f) + EPS); }
;             u32x2 pk[2][4];
; #pragma unroll
;             for (int n = 0; n < 2; ++n) {
;                 f32x4 g[4];
;                 {   const PG8_LAS unsigned char* wq = wl + (8 * fq + 4 * n) * 4;
;                     const f32x4 w0 = *(const PG8_LAS f32x4*)(wq), w1 = *(const PG8_LAS f32x4*)(wq + 256), w2 = *(const PG8_LAS f32x4*)(wq + 512), bb = *(const PG8_LAS f32x4*)(wq + 768);
;                     const f32x4 x0 = acc[ai][0][0][n] * rstd[0], x1 = acc[ai][0][1][n] * rstd[1], x2 = acc[ai][0][2][n] * rstd[2], x3 = acc[ai][0][3][n] * rstd[3];
;                     acc[ai][0][0][n] = x0; acc[ai][0][1][n] = x1; acc[ai][0][2][n] = x2; acc[ai][0][3][n] = x3;
;                     f32x4 p1, p2;
; #pragma unroll
;                     for (int c = 0; c < 4; ++c) { p1[c] = row_up1(x3[c]); p2[c] = row_up1(x2[c]); }
;                     g[0] = bb + w2 * x0 + w1 * p1 + w0 * p2; g[1] = bb + w2 * x1 + w1 * x0 + w0 * p1;
;                     g[2] = bb + w2 * x2 + w1 * x1 + w0 * x0; g[3] = bb + w2 * x3 + w1 * x2 + w0 * x1;
.LBB0_754:
	s_or_b64 exec, exec, s[8:9]
	s_nop 0
	v_add_u32_e32 v66, 0x80, v148
	v_ashrrev_i32_e32 v67, 31, v66
	v_lshlrev_b64 v[68:69], 6, v[66:67]
	v_lshl_add_u64 v[70:71], v[138:139], 0, v[68:69]
	v_add_u32_e32 v68, 0x81, v148
	v_ashrrev_i32_e32 v69, 31, v68
	v_lshlrev_b64 v[72:73], 6, v[68:69]
	v_lshl_add_u64 v[72:73], v[138:139], 0, v[72:73]
	global_load_dwordx4 v[74:77], v[70:71], off
	global_load_dwordx4 v[78:81], v[72:73], off
	v_add_u32_e32 v70, 0x82, v148
	v_ashrrev_i32_e32 v71, 31, v70
	v_lshlrev_b64 v[72:73], 6, v[70:71]
	v_lshl_add_u64 v[72:73], v[138:139], 0, v[72:73]
	global_load_dwordx4 v[82:85], v[72:73], off
	v_add_u32_e32 v72, 0x83, v148
	v_ashrrev_i32_e32 v73, 31, v72
	v_lshlrev_b64 v[86:87], 6, v[72:73]
	v_lshl_add_u64 v[86:87], v[138:139], 0, v[86:87]
	global_load_dwordx4 v[86:89], v[86:87], off
	s_waitcnt vmcnt(3)
	v_mov_b32_e32 v90, v75
	v_mov_b32_e32 v91, v76
	v_mov_b32_e32 v75, v77
	s_waitcnt vmcnt(2)
	v_mov_b32_e32 v76, v79
	v_mov_b32_e32 v77, v80
	v_mov_b32_e32 v79, v81
	s_waitcnt vmcnt(1)
	v_mov_b32_e32 v80, v83
	v_mov_b32_e32 v81, v84
	v_mov_b32_e32 v83, v85
	v_pk_add_f32 v[74:75], v[90:91], v[74:75]
	v_pk_add_f32 v[76:77], v[76:77], v[78:79]
	s_waitcnt vmcnt(0)
	v_mov_b32_e32 v84, v87
	v_mov_b32_e32 v85, v88
	v_mov_b32_e32 v87, v89
	v_pk_add_f32 v[78:79], v[80:81], v[82:83]
	v_pk_add_f32 v[80:81], v[84:85], v[86:87]
	v_mov_b32_e32 v82, v76
	v_mov_b32_e32 v83, v74
	v_mov_b32_e32 v74, v77
	v_mov_b32_e32 v76, v80
	v_mov_b32_e32 v77, v78
	v_mov_b32_e32 v78, v81
	v_pk_add_f32 v[74:75], v[82:83], v[74:75]
	v_pk_add_f32 v[76:77], v[76:77], v[78:79]
	ds_bpermute_b32 v79, v149, v75
	ds_bpermute_b32 v78, v149, v74
	ds_bpermute_b32 v81, v149, v77
	ds_bpermute_b32 v80, v149, v76
	v_mov_b64_e32 v[82:83], s[38:39]
	s_waitcnt lgkmcnt(2)
	v_pk_add_f32 v[84:85], v[74:75], v[78:79]
	ds_bpermute_b32 v89, v151, v85
	s_waitcnt lgkmcnt(1)
	v_pk_add_f32 v[86:87], v[76:77], v[80:81]
	ds_bpermute_b32 v88, v151, v84
	ds_bpermute_b32 v99, v151, v87
	ds_bpermute_b32 v98, v151, v86
	ds_read_b128 v[74:77], v195
	ds_read_b128 v[78:81], v195 offset:256
	ds_read_b128 v[90:93], v195 offset:512
	ds_read_b128 v[94:97], v195 offset:768
	s_waitcnt lgkmcnt(6)
	v_pk_add_f32 v[84:85], v[84:85], v[88:89]
	s_nop 0
	v_pk_fma_f32 v[84:85], v[84:85], s[24:25], v[82:83] op_sel_hi:[1,0,0]
	s_waitcnt lgkmcnt(4)
	v_pk_add_f32 v[86:87], v[86:87], v[98:99]
	v_mul_f32_e32 v67, 0x4b800000, v85
	v_pk_fma_f32 v[82:83], v[86:87], s[24:25], v[82:83] op_sel_hi:[1,0,0]
	v_cmp_gt_f32_e32 vcc, s63, v85
	v_mul_f32_e32 v73, 0x4b800000, v82
	v_cmp_gt_f32_e64 s[12:13], s63, v82
	v_mul_f32_e32 v69, 0x4b800000, v84
	v_mul_f32_e32 v71, 0x4b800000, v83
	v_cndmask_b32_e32 v67, v85, v67, vcc
	v_cmp_gt_f32_e64 s[8:9], s63, v84
	v_cmp_gt_f32_e64 s[10:11], s63, v83
	v_cndmask_b32_e64 v73, v82, v73, s[12:13]
	v_cndmask_b32_e64 v69, v84, v69, s[8:9]
	v_cndmask_b32_e64 v71, v83, v71, s[10:11]
	v_rsq_f32_e32 v67, v67
	v_rsq_f32_e32 v73, v73
	v_rsq_f32_e32 v69, v69
	v_rsq_f32_e32 v71, v71
	v_mul_f32_e32 v82, 0x45800000, v67
	v_mul_f32_e32 v85, 0x45800000, v73
	v_mul_f32_e32 v83, 0x45800000, v69
	v_mul_f32_e32 v84, 0x45800000, v71
	v_cndmask_b32_e32 v88, v67, v82, vcc
	v_cndmask_b32_e64 v82, v73, v85, s[12:13]
	v_cndmask_b32_e64 v84, v71, v84, s[10:11]
	v_pk_mul_f32 v[60:61], v[60:61], v[88:89] op_sel_hi:[1,0]
	v_pk_mul_f32 v[48:49], v[48:49], v[82:83] op_sel_hi:[1,0]
	v_pk_mul_f32 v[52:53], v[52:53], v[84:85] op_sel_hi:[1,0]
	s_waitcnt lgkmcnt(0)
	v_pk_fma_f32 v[108:109], v[90:91], v[60:61], v[94:95]
	v_mov_b32_dpp v98, v48 row_shr:1 row_mask:0xf bank_mask:0xf bound_ctrl:1
	v_mov_b32_dpp v99, v49 row_shr:1 row_mask:0xf bank_mask:0xf bound_ctrl:1
	v_mov_b32_dpp v100, v52 row_shr:1 row_mask:0xf bank_mask:0xf bound_ctrl:1
	v_mov_b32_dpp v101, v53 row_shr:1 row_mask:0xf bank_mask:0xf bound_ctrl:1
	v_pk_fma_f32 v[108:109], v[78:79], v[98:99], v[108:109]
	v_cndmask_b32_e64 v86, v69, v83, s[8:9]
	v_pk_fma_f32 v[100:101], v[74:75], v[100:101], v[108:109]
	v_pk_mul_f32 v[62:63], v[62:63], v[88:89] op_sel_hi:[1,0]
	v_exp_f32_e32 v242, v100
	v_pk_mul_f32 v[50:51], v[50:51], v[82:83] op_sel_hi:[1,0]
	v_exp_f32_e32 v243, v101
	v_pk_mul_f32 v[56:57], v[56:57], v[86:87] op_sel_hi:[1,0]
	v_pk_mul_f32 v[54:55], v[54:55], v[84:85] op_sel_hi:[1,0]
	v_mov_b32_dpp v102, v50 row_shr:1 row_mask:0xf bank_mask:0xf bound_ctrl:1
	v_mov_b32_dpp v103, v51 row_shr:1 row_mask:0xf bank_mask:0xf bound_ctrl:1
	v_pk_fma_f32 v[106:107], v[92:93], v[62:63], v[96:97]
	v_mov_b32_dpp v104, v54 row_shr:1 row_mask:0xf bank_mask:0xf bound_ctrl:1
	v_mov_b32_dpp v105, v55 row_shr:1 row_mask:0xf bank_mask:0xf bound_ctrl:1
	v_pk_fma_f32 v[112:113], v[90:91], v[56:57], v[94:95]
	v_pk_fma_f32 v[106:107], v[80:81], v[102:103], v[106:107]
	v_pk_fma_f32 v[108:109], v[90:91], v[52:53], v[94:95]
	v_pk_fma_f32 v[90:91], v[90:91], v[48:49], v[94:95]
	v_pk_fma_f32 v[112:113], v[78:79], v[60:61], v[112:113]
	v_pk_fma_f32 v[104:105], v[76:77], v[104:105], v[106:107]
	v_pk_fma_f32 v[108:109], v[78:79], v[56:57], v[108:109]
	v_pk_fma_f32 v[78:79], v[78:79], v[52:53], v[90:91]
	v_pk_fma_f32 v[98:99], v[74:75], v[98:99], v[112:113]
	v_pk_fma_f32 v[108:109], v[74:75], v[60:61], v[108:109]
	v_pk_fma_f32 v[116:117], v[74:75], v[56:57], v[78:79]
	v_pk_add_f32 v[242:243], v[242:243], v[250:251]
	v_rcp_f32_e32 v74, v242
	v_exp_f32_e32 v244, v104
	v_exp_f32_e32 v245, v105
	v_pk_mul_f32 v[58:59], v[58:59], v[86:87] op_sel_hi:[1,0]
	v_pk_fma_f32 v[106:107], v[92:93], v[54:55], v[96:97]
	v_pk_fma_f32 v[110:111], v[92:93], v[58:59], v[96:97]
	v_pk_fma_f32 v[92:93], v[92:93], v[50:51], v[96:97]
	v_pk_fma_f32 v[110:111], v[80:81], v[62:63], v[110:111]
; #define PG8_LAS __attribute__((address_space(3)))
; __device__ __forceinline__ unsigned pk2(float a, float b) { return pg8::cvt_pk_bf16(a, b); }
; __device__ __forceinline__ float row_up1(float v) { return dpp_mov<0x111>(v); }
; __device__ __forceinline__ float siluf_(float x) { return x * __builtin_amdgcn_rcpf(1.0f + __builtin_amdgcn_exp2f(x * -1.4426950408889634f)); }
;     __device__ __forceinline__ void operator()(f32x4 (&acc)[2][2][4][2], const pg8::Unit& u, int wr, int wc, int fr, int fq) const {
;     ...
;                     g[0] = bb + w2 * x0 + w1 * p1 + w0 * p2; g[1] = bb + w2 * x1 + w1 * x0 + w0 * p1;
;                     g[2] = bb + w2 * x2 + w1 * x1 + w0 * x0; g[3] = bb + w2 * x3 + w1 * x2 + w0 * x1;
; #pragma unroll
;                     for (int m = 0; m < 4; ++m)
; #pragma unroll
;                         for (int c = 0; c < 4; ++c) g[m][c] = siluf_(g[m][c]);
;                 }
;                 __builtin_amdgcn_sched_barrier(0);
;                 {   const PG8_LAS unsigned char* wq = wl + 128 + (8 * fq + 4 * n) * 4;
;                     const f32x4 w0 = *(const PG8_LAS f32x4*)(wq), w1 = *(const PG8_LAS f32x4*)(wq + 256), w2 = *(const PG8_LAS f32x4*)(wq + 512), bb = *(const PG8_LAS f32x4*)(wq + 768);
;                     const f32x4 x0 = acc[ai][1][0][n] * rstd[0], x1 = acc[ai][1][1][n] * rstd[1], x2 = acc[ai][1][2][n] * rstd[2], x3 = acc[ai][1][3][n] * rstd[3];
;                     acc[ai][1][0][n] = x0; acc[ai][1][1][n] = x1; acc[ai][1][2][n] = x2; acc[ai][1][3][n] = x3;
;                     f32x4 p1, p2;
; #pragma unroll
;                     for (int c = 0; c < 4; ++c) { p1[c] = row_up1(x3[c]); p2[c] = row_up1(x2[c]); }
;                     g[0] *= bb + w2 * x0 + w1 * p1 + w0 * p2; g[1] *= bb + w2 * x1 + w1 * x0 + w0 * p1;
;                     g[2] *= bb + w2 * x2 + w1 * x1 + w0 * x0; g[3] *= bb + w2 * x3 + w1 * x2 + w0 * x1;
;                 }
; #pragma unroll
;                 for (int m = 0; m < 4; ++m) { pk[n][m].x = pk2(g[m][0], g[m][1]); pk[n][m].y = pk2(g[m][2], g[m][3]); }
	v_pk_fma_f32 v[106:107], v[80:81], v[58:59], v[106:107]
	v_pk_fma_f32 v[80:81], v[80:81], v[54:55], v[92:93]
	v_rcp_f32_e32 v75, v243
	v_pk_fma_f32 v[102:103], v[76:77], v[102:103], v[110:111]
	v_pk_fma_f32 v[106:107], v[76:77], v[62:63], v[106:107]
	v_pk_fma_f32 v[114:115], v[76:77], v[58:59], v[80:81]
	v_pk_add_f32 v[244:245], v[244:245], v[250:251]
	v_rcp_f32_e32 v76, v244
	v_rcp_f32_e32 v77, v245
	v_exp_f32_e32 v246, v98
	v_exp_f32_e32 v247, v99
	v_pk_mul_f32 v[118:119], v[100:101], v[74:75]
	v_pk_add_f32 v[246:247], v[246:247], v[250:251]
	v_rcp_f32_e32 v74, v246
	v_exp_f32_e32 v248, v102
	v_exp_f32_e32 v249, v103
	v_rcp_f32_e32 v75, v247
	v_pk_mul_f32 v[120:121], v[104:105], v[76:77]
	v_pk_add_f32 v[248:249], v[248:249], v[250:251]
	v_rcp_f32_e32 v76, v248
	v_rcp_f32_e32 v77, v249
	v_exp_f32_e32 v240, v108
	v_exp_f32_e32 v241, v109
	v_pk_mul_f32 v[122:123], v[98:99], v[74:75]
	v_pk_add_f32 v[240:241], v[240:241], v[250:251]
	v_rcp_f32_e32 v74, v240
	v_exp_f32_e32 v242, v106
	v_exp_f32_e32 v243, v107
	v_rcp_f32_e32 v75, v241
	v_pk_add_f32 v[242:243], v[242:243], v[250:251]
	v_rcp_f32_e32 v78, v242
	v_exp_f32_e32 v244, v116
	v_exp_f32_e32 v245, v117
	v_rcp_f32_e32 v79, v243
	v_pk_add_f32 v[244:245], v[244:245], v[250:251]
	v_rcp_f32_e32 v124, v244
	v_exp_f32_e32 v246, v114
	v_exp_f32_e32 v247, v115
	v_rcp_f32_e32 v125, v245
	v_pk_add_f32 v[246:247], v[246:247], v[250:251]
	v_rcp_f32_e32 v126, v246
	v_rcp_f32_e32 v127, v247
	v_pk_mul_f32 v[148:149], v[102:103], v[76:77]
	v_pk_mul_f32 v[150:151], v[108:109], v[74:75]
	v_pk_mul_f32 v[154:155], v[106:107], v[78:79]
	ds_read_b128 v[98:101], v195 offset:128
	ds_read_b128 v[102:105], v195 offset:384
	ds_read_b128 v[106:109], v195 offset:640
	ds_read_b128 v[110:113], v195 offset:896
	v_pk_mul_f32 v[90:91], v[44:45], v[88:89] op_sel_hi:[1,0]
	v_pk_mul_f32 v[78:79], v[32:33], v[82:83] op_sel_hi:[1,0]
	v_pk_mul_f32 v[94:95], v[36:37], v[84:85] op_sel_hi:[1,0]
	v_pk_mul_f32 v[74:75], v[40:41], v[86:87] op_sel_hi:[1,0]
	v_mov_b32_dpp v32, v78 row_shr:1 row_mask:0xf bank_mask:0xf bound_ctrl:1
	v_mov_b32_dpp v33, v79 row_shr:1 row_mask:0xf bank_mask:0xf bound_ctrl:1
	s_waitcnt lgkmcnt(0)
	v_pk_fma_f32 v[44:45], v[90:91], v[106:107], v[110:111]
	v_pk_mul_f32 v[80:81], v[34:35], v[82:83] op_sel_hi:[1,0]
	v_mov_b32_dpp v34, v94 row_shr:1 row_mask:0xf bank_mask:0xf bound_ctrl:1
	v_mov_b32_dpp v35, v95 row_shr:1 row_mask:0xf bank_mask:0xf bound_ctrl:1
	v_pk_fma_f32 v[44:45], v[102:103], v[32:33], v[44:45]
	v_pk_mul_f32 v[92:93], v[46:47], v[88:89] op_sel_hi:[1,0]
	v_pk_fma_f32 v[34:35], v[98:99], v[34:35], v[44:45]
	v_pk_fma_f32 v[44:45], v[74:75], v[106:107], v[110:111]
	v_pk_mul_f32 v[96:97], v[38:39], v[84:85] op_sel_hi:[1,0]
	v_mov_b32_dpp v36, v80 row_shr:1 row_mask:0xf bank_mask:0xf bound_ctrl:1
	v_mov_b32_dpp v37, v81 row_shr:1 row_mask:0xf bank_mask:0xf bound_ctrl:1
	v_pk_fma_f32 v[46:47], v[92:93], v[108:109], v[112:113]
	v_pk_fma_f32 v[44:45], v[90:91], v[102:103], v[44:45]
	v_pk_mul_f32 v[76:77], v[42:43], v[86:87] op_sel_hi:[1,0]
	v_mov_b32_dpp v38, v96 row_shr:1 row_mask:0xf bank_mask:0xf bound_ctrl:1
	v_mov_b32_dpp v39, v97 row_shr:1 row_mask:0xf bank_mask:0xf bound_ctrl:1
	v_pk_fma_f32 v[46:47], v[104:105], v[36:37], v[46:47]
	v_pk_fma_f32 v[32:33], v[98:99], v[32:33], v[44:45]
	v_pk_fma_f32 v[44:45], v[94:95], v[106:107], v[110:111]
	v_pk_fma_f32 v[38:39], v[100:101], v[38:39], v[46:47]
	v_pk_fma_f32 v[46:47], v[76:77], v[108:109], v[112:113]
	v_pk_fma_f32 v[44:45], v[74:75], v[102:103], v[44:45]
	v_pk_fma_f32 v[46:47], v[92:93], v[104:105], v[46:47]
	v_pk_fma_f32 v[44:45], v[90:91], v[98:99], v[44:45]
	v_pk_mul_f32 v[42:43], v[114:115], v[126:127]
	v_pk_fma_f32 v[36:37], v[100:101], v[36:37], v[46:47]
	v_pk_fma_f32 v[46:47], v[96:97], v[108:109], v[112:113]
	v_pk_mul_f32 v[114:115], v[44:45], v[150:151]
	v_pk_fma_f32 v[44:45], v[78:79], v[106:107], v[110:111]
	v_pk_fma_f32 v[106:107], v[80:81], v[108:109], v[112:113]
	v_pk_fma_f32 v[46:47], v[76:77], v[104:105], v[46:47]
	v_pk_fma_f32 v[104:105], v[96:97], v[104:105], v[106:107]
	v_pk_fma_f32 v[44:45], v[94:95], v[102:103], v[44:45]
	v_pk_mul_f32 v[40:41], v[116:117], v[124:125]
	v_pk_fma_f32 v[46:47], v[92:93], v[100:101], v[46:47]
	v_pk_fma_f32 v[44:45], v[74:75], v[98:99], v[44:45]
	v_pk_fma_f32 v[98:99], v[76:77], v[100:101], v[104:105]
	v_pk_mul_f32 v[38:39], v[120:121], v[38:39]
	v_pk_mul_f32 v[34:35], v[118:119], v[34:35]
	v_pk_mul_f32 v[36:37], v[148:149], v[36:37]
	v_pk_mul_f32 v[32:33], v[122:123], v[32:33]
	v_pk_mul_f32 v[46:47], v[46:47], v[154:155]
	v_pk_mul_f32 v[42:43], v[98:99], v[42:43]
	v_pk_mul_f32 v[98:99], v[44:45], v[40:41]
	v_cvt_pk_bf16_f32 v44, v34, v35
	v_cvt_pk_bf16_f32 v45, v38, v39
	v_cvt_pk_bf16_f32 v40, v32, v33
	v_cvt_pk_bf16_f32 v41, v36, v37
	v_cvt_pk_bf16_f32 v36, v114, v115
	v_cvt_pk_bf16_f32 v37, v46, v47
	s_nop 0
	v_cvt_pk_bf16_f32 v32, v98, v99
	v_cvt_pk_bf16_f32 v33, v42, v43
	ds_read_b128 v[102:105], v195 offset:16
	ds_read_b128 v[106:109], v195 offset:272
	ds_read_b128 v[110:113], v195 offset:528
	ds_read_b128 v[114:117], v195 offset:784
	v_pk_mul_f32 v[98:99], v[16:17], v[88:89] op_sel_hi:[1,0]
	v_pk_mul_f32 v[16:17], v[20:21], v[86:87] op_sel_hi:[1,0]
	v_pk_mul_f32 v[20:21], v[28:29], v[82:83] op_sel_hi:[1,0]
	v_pk_mul_f32 v[24:25], v[24:25], v[84:85] op_sel_hi:[1,0]
	s_waitcnt lgkmcnt(0)
; #define PG8_LAS __attribute__((address_space(3)))
; __device__ __forceinline__ unsigned pk2(float a, float b) { return pg8::cvt_pk_bf16(a, b); }
; __device__ __forceinline__ float row_up1(float v) { return dpp_mov<0x111>(v); }
; __device__ __forceinline__ float siluf_(float x) { return x * __builtin_amdgcn_rcpf(1.0f + __builtin_amdgcn_exp2f(x * -1.4426950408889634f)); }
;     __device__ __forceinline__ void operator()(f32x4 (&acc)[2][2][4][2], const pg8::Unit& u, int wr, int wc, int fr, int fq) const {
;     ...
;                     g[0] = bb + w2 * x0 + w1 * p1 + w0 * p2; g[1] = bb + w2 * x1 + w1 * x0 + w0 * p1;
;                     g[2] = bb + w2 * x2 + w1 * x1 + w0 * x0; g[3] = bb + w2 * x3 + w1 * x2 + w0 * x1;
; #pragma unroll
;                     for (int m = 0; m < 4; ++m)
; #pragma unroll
;                         for (int c = 0; c < 4; ++c) g[m][c] = siluf_(g[m][c]);
;                 }
;                 __builtin_amdgcn_sched_barrier(0);
;                 {   const PG8_LAS unsigned char* wq = wl + 128 + (8 * fq + 4 * n) * 4;
;                     const f32x4 w0 = *(const PG8_LAS f32x4*)(wq), w1 = *(const PG8_LAS f32x4*)(wq + 256), w2 = *(const PG8_LAS f32x4*)(wq + 512), bb = *(const PG8_LAS f32x4*)(wq + 768);
;                     const f32x4 x0 = acc[ai][1][0][n] * rstd[0], x1 = acc[ai][1][1][n] * rstd[1], x2 = acc[ai][1][2][n] * rstd[2], x3 = acc[ai][1][3][n] * rstd[3];
;                     acc[ai][1][0][n] = x0; acc[ai][1][1][n] = x1; acc[ai][1][2][n] = x2; acc[ai][1][3][n] = x3;
;                     f32x4 p1, p2;
; #pragma unroll
;                     for (int c = 0; c < 4; ++c) { p1[c] = row_up1(x3[c]); p2[c] = row_up1(x2[c]); }
;                     g[0] *= bb + w2 * x0 + w1 * p1 + w0 * p2; g[1] *= bb + w2 * x1 + w1 * x0 + w0 * p1;
;                     g[2] *= bb + w2 * x2 + w1 * x1 + w0 * x0; g[3] *= bb + w2 * x3 + w1 * x2 + w0 * x1;
;                 }
; #pragma unroll
;                 for (int m = 0; m < 4; ++m) { pk[n][m].x = pk2(g[m][0], g[m][1]); pk[n][m].y = pk2(g[m][2], g[m][3]); }
;                 __builtin_amdgcn_sched_barrier(0);
;             }
; #pragma unroll
;             for (int m = 0; m < 4; ++m) if (fr != 0 || m >= 2) {
	v_pk_fma_f32 v[46:47], v[98:99], v[110:111], v[114:115]
	v_mov_b32_dpp v28, v20 row_shr:1 row_mask:0xf bank_mask:0xf bound_ctrl:1
	v_mov_b32_dpp v29, v21 row_shr:1 row_mask:0xf bank_mask:0xf bound_ctrl:1
	v_pk_mul_f32 v[100:101], v[18:19], v[88:89] op_sel_hi:[1,0]
	v_pk_mul_f32 v[18:19], v[22:23], v[86:87] op_sel_hi:[1,0]
	v_pk_mul_f32 v[22:23], v[30:31], v[82:83] op_sel_hi:[1,0]
	v_mov_b32_dpp v30, v24 row_shr:1 row_mask:0xf bank_mask:0xf bound_ctrl:1
	v_mov_b32_dpp v31, v25 row_shr:1 row_mask:0xf bank_mask:0xf bound_ctrl:1
	v_pk_fma_f32 v[46:47], v[106:107], v[28:29], v[46:47]
	v_pk_mul_f32 v[26:27], v[26:27], v[84:85] op_sel_hi:[1,0]
	v_pk_fma_f32 v[30:31], v[102:103], v[30:31], v[46:47]
	v_pk_fma_f32 v[46:47], v[16:17], v[110:111], v[114:115]
	v_exp_f32_e32 v248, v30
	v_exp_f32_e32 v249, v31
	v_mov_b32_dpp v34, v22 row_shr:1 row_mask:0xf bank_mask:0xf bound_ctrl:1
	v_mov_b32_dpp v35, v23 row_shr:1 row_mask:0xf bank_mask:0xf bound_ctrl:1
	v_pk_fma_f32 v[42:43], v[100:101], v[112:113], v[116:117]
	v_pk_fma_f32 v[46:47], v[98:99], v[106:107], v[46:47]
	v_mov_b32_dpp v38, v26 row_shr:1 row_mask:0xf bank_mask:0xf bound_ctrl:1
	v_mov_b32_dpp v39, v27 row_shr:1 row_mask:0xf bank_mask:0xf bound_ctrl:1
	v_pk_fma_f32 v[42:43], v[108:109], v[34:35], v[42:43]
	v_pk_fma_f32 v[28:29], v[102:103], v[28:29], v[46:47]
	v_pk_fma_f32 v[46:47], v[24:25], v[110:111], v[114:115]
	v_pk_fma_f32 v[110:111], v[20:21], v[110:111], v[114:115]
	v_pk_fma_f32 v[38:39], v[104:105], v[38:39], v[42:43]
	v_pk_fma_f32 v[46:47], v[16:17], v[106:107], v[46:47]
	v_pk_fma_f32 v[106:107], v[24:25], v[106:107], v[110:111]
	v_pk_fma_f32 v[46:47], v[98:99], v[102:103], v[46:47]
	v_pk_fma_f32 v[120:121], v[16:17], v[102:103], v[106:107]
	v_pk_add_f32 v[248:249], v[248:249], v[250:251]
	v_rcp_f32_e32 v102, v248
	v_exp_f32_e32 v240, v38
	v_pk_fma_f32 v[42:43], v[18:19], v[112:113], v[116:117]
	v_exp_f32_e32 v241, v39
	v_pk_fma_f32 v[42:43], v[100:101], v[108:109], v[42:43]
	v_rcp_f32_e32 v103, v249
	v_pk_fma_f32 v[34:35], v[104:105], v[34:35], v[42:43]
	v_pk_fma_f32 v[42:43], v[26:27], v[112:113], v[116:117]
	v_pk_fma_f32 v[112:113], v[22:23], v[112:113], v[116:117]
	v_pk_fma_f32 v[42:43], v[18:19], v[108:109], v[42:43]
	v_pk_fma_f32 v[108:109], v[26:27], v[108:109], v[112:113]
	v_pk_fma_f32 v[42:43], v[100:101], v[104:105], v[42:43]
	v_pk_fma_f32 v[118:119], v[18:19], v[104:105], v[108:109]
	v_pk_add_f32 v[240:241], v[240:241], v[250:251]
	v_rcp_f32_e32 v104, v240
	v_rcp_f32_e32 v105, v241
	v_exp_f32_e32 v242, v34
	v_pk_mul_f32 v[122:123], v[30:31], v[102:103]
	v_exp_f32_e32 v243, v35
	v_exp_f32_e32 v244, v28
	v_exp_f32_e32 v245, v29
	v_pk_add_f32 v[242:243], v[242:243], v[250:251]
	v_rcp_f32_e32 v102, v242
	v_pk_add_f32 v[244:245], v[244:245], v[250:251]
	v_rcp_f32_e32 v103, v243
	v_rcp_f32_e32 v30, v244
	v_rcp_f32_e32 v31, v245
	v_exp_f32_e32 v246, v46
	v_exp_f32_e32 v247, v47
	v_pk_mul_f32 v[124:125], v[28:29], v[30:31]
	v_pk_add_f32 v[246:247], v[246:247], v[250:251]
	v_exp_f32_e32 v248, v120
	v_exp_f32_e32 v249, v121
	v_exp_f32_e32 v240, v42
	v_exp_f32_e32 v241, v43
	v_pk_add_f32 v[248:249], v[248:249], v[250:251]
	v_rcp_f32_e32 v126, v248
	v_pk_add_f32 v[240:241], v[240:241], v[250:251]
	v_exp_f32_e32 v242, v118
	v_rcp_f32_e32 v28, v246
	v_rcp_f32_e32 v29, v247
	v_rcp_f32_e32 v30, v240
	v_rcp_f32_e32 v31, v241
	v_exp_f32_e32 v243, v119
	v_rcp_f32_e32 v127, v249
	v_pk_mul_f32 v[38:39], v[38:39], v[104:105]
	v_pk_add_f32 v[242:243], v[242:243], v[250:251]
	v_rcp_f32_e32 v148, v242
	v_pk_mul_f32 v[34:35], v[34:35], v[102:103]
	v_pk_mul_f32 v[46:47], v[46:47], v[28:29]
	v_pk_mul_f32 v[42:43], v[42:43], v[30:31]
	v_rcp_f32_e32 v149, v243
	ds_read_b128 v[102:105], v195 offset:144
	ds_read_b128 v[106:109], v195 offset:400
	ds_read_b128 v[110:113], v195 offset:656
	ds_read_b128 v[114:117], v195 offset:912
	v_pk_mul_f32 v[30:31], v[2:3], v[88:89] op_sel_hi:[1,0]
	v_pk_mul_f32 v[28:29], v[0:1], v[88:89] op_sel_hi:[1,0]
	v_pk_mul_f32 v[2:3], v[6:7], v[86:87] op_sel_hi:[1,0]
	v_pk_mul_f32 v[0:1], v[4:5], v[86:87] op_sel_hi:[1,0]
	v_pk_mul_f32 v[6:7], v[14:15], v[82:83] op_sel_hi:[1,0]
	v_pk_mul_f32 v[4:5], v[12:13], v[82:83] op_sel_hi:[1,0]
	v_pk_mul_f32 v[10:11], v[10:11], v[84:85] op_sel_hi:[1,0]
	v_pk_mul_f32 v[8:9], v[8:9], v[84:85] op_sel_hi:[1,0]
	v_mov_b32_dpp v12, v4 row_shr:1 row_mask:0xf bank_mask:0xf bound_ctrl:1
	v_mov_b32_dpp v13, v5 row_shr:1 row_mask:0xf bank_mask:0xf bound_ctrl:1
	v_mov_b32_dpp v82, v6 row_shr:1 row_mask:0xf bank_mask:0xf bound_ctrl:1
	v_mov_b32_dpp v83, v7 row_shr:1 row_mask:0xf bank_mask:0xf bound_ctrl:1
	v_pk_mul_f32 v[86:87], v[120:121], v[126:127]
	v_pk_mul_f32 v[88:89], v[118:119], v[148:149]
	s_waitcnt lgkmcnt(0)
	v_pk_fma_f32 v[118:119], v[28:29], v[110:111], v[114:115]
	v_pk_fma_f32 v[120:121], v[30:31], v[112:113], v[116:117]
	v_mov_b32_dpp v14, v8 row_shr:1 row_mask:0xf bank_mask:0xf bound_ctrl:1
	v_mov_b32_dpp v15, v9 row_shr:1 row_mask:0xf bank_mask:0xf bound_ctrl:1
	v_mov_b32_dpp v84, v10 row_shr:1 row_mask:0xf bank_mask:0xf bound_ctrl:1
	v_mov_b32_dpp v85, v11 row_shr:1 row_mask:0xf bank_mask:0xf bound_ctrl:1
	v_pk_fma_f32 v[120:121], v[108:109], v[82:83], v[120:121]
	v_pk_fma_f32 v[118:119], v[106:107], v[12:13], v[118:119]
	v_pk_fma_f32 v[84:85], v[104:105], v[84:85], v[120:121]
	v_pk_fma_f32 v[14:15], v[102:103], v[14:15], v[118:119]
	v_pk_fma_f32 v[118:119], v[2:3], v[112:113], v[116:117]
	v_pk_mul_f32 v[38:39], v[38:39], v[84:85]
	v_pk_fma_f32 v[84:85], v[0:1], v[110:111], v[114:115]
	v_pk_fma_f32 v[118:119], v[30:31], v[108:109], v[118:119]
	v_pk_fma_f32 v[84:85], v[28:29], v[106:107], v[84:85]
	v_pk_fma_f32 v[82:83], v[104:105], v[82:83], v[118:119]
	v_pk_fma_f32 v[12:13], v[102:103], v[12:13], v[84:85]
	v_pk_mul_f32 v[34:35], v[34:35], v[82:83]
	v_pk_fma_f32 v[82:83], v[8:9], v[110:111], v[114:115]
	v_pk_fma_f32 v[84:85], v[10:11], v[112:113], v[116:117]
	v_pk_fma_f32 v[82:83], v[0:1], v[106:107], v[82:83]
	v_pk_fma_f32 v[84:85], v[2:3], v[108:109], v[84:85]
	v_pk_fma_f32 v[82:83], v[28:29], v[102:103], v[82:83]
	v_pk_fma_f32 v[84:85], v[30:31], v[104:105], v[84:85]
	v_pk_mul_f32 v[82:83], v[46:47], v[82:83]
	v_pk_mul_f32 v[84:85], v[42:43], v[84:85]
	v_pk_fma_f32 v[42:43], v[4:5], v[110:111], v[114:115]
	v_pk_fma_f32 v[46:47], v[6:7], v[112:113], v[116:117]
	v_pk_fma_f32 v[42:43], v[8:9], v[106:107], v[42:43]
	v_pk_fma_f32 v[46:47], v[10:11], v[108:109], v[46:47]
	v_pk_fma_f32 v[42:43], v[0:1], v[102:103], v[42:43]
	v_pk_fma_f32 v[46:47], v[2:3], v[104:105], v[46:47]
	v_pk_mul_f32 v[14:15], v[122:123], v[14:15]
	v_pk_mul_f32 v[12:13], v[124:125], v[12:13]
	v_pk_mul_f32 v[88:89], v[88:89], v[46:47]
	v_pk_mul_f32 v[86:87], v[86:87], v[42:43]
	v_cvt_pk_bf16_f32 v46, v14, v15
	v_cvt_pk_bf16_f32 v47, v38, v39
	v_cvt_pk_bf16_f32 v42, v12, v13
	v_cvt_pk_bf16_f32 v43, v34, v35
	v_cvt_pk_bf16_f32 v38, v82, v83
	v_cvt_pk_bf16_f32 v39, v84, v85
	s_nop 0
	v_cvt_pk_bf16_f32 v34, v86, v87
	v_cvt_pk_bf16_f32 v35, v88, v89
	s_and_saveexec_b64 s[8:9], s[0:1]
	s_cbranch_execz .LBB0_756
;     __device__ __forceinline__ void operator()(f32x4 (&acc)[2][2][4][2], const pg8::Unit& u, int wr, int wc, int fr, int fq) const {
;     ...
;             for (int m = 0; m < 4; ++m) if (fr != 0 || m >= 2) {
;                 u32x4 w; w.x = pk[0][m].x; w.y = pk[0][m].y; w.z = pk[1][m].x; w.w = pk[1][m].y;
;                 *(u32x4*)(ACT + (size_t)(tb + m) * DFF + colj) = w; }
	v_mov_b64_e32 v[12:13], s[22:23]
	v_mad_i64_i32 v[14:15], s[10:11], v66, s56, v[12:13]
	v_mad_i64_i32 v[12:13], s[10:11], v68, s56, v[12:13]
	v_lshl_add_u64 v[14:15], v[14:15], 0, v[64:65]
	v_lshl_add_u64 v[12:13], v[12:13], 0, v[64:65]
	global_store_dwordx4 v[14:15], v[44:47], off
	global_store_dwordx4 v[12:13], v[40:43], off
